# scan loader: zero-initialisation of the previous-token registers and the sample-job decode block are branched around when no lane needs them
# speedup vs baseline: 1.0050x; 1.0012x over previous
; __device__ __forceinline__ float bflo(unsigned w) { return __uint_as_float(w << 16); }
; __device__ __forceinline__ Job job_decode(int J, int ci) {
;     Job j;
;     if (J < 256) { const int pair = J >> 2; j.is_s = 0; j.seq = pair >> 3; j.h = pair & 7; j.rs = J & 3; j.tok0 = j.seq * SEQ + ci * SC_CH; j.nsteps = SC_CH; j.first = ci == 0; j.last = ci == SEQ / SC_CH - 1; }
;     else { const int Js = J - 256, pair = Js >> 2; j.is_s = 1; j.seq = pair >> 3; j.h = pair & 7; j.rs = Js & 3; j.tok0 = T_P + j.seq * DSEQ; j.nsteps = 8; j.first = 1; j.last = 1; }
;     return j;
; }
; __device__ __forceinline__ void scan_issue(const ScanPtrs& Q, int J, int ci, int ltid, LStage& L, int toff) {
;     const Job jb = job_decode(J, ci);
;     const int tt = (ltid >> 4) + toff, c = (ltid & 15) * 4;
;     if (tt < jb.nsteps) {
;         const int tok = jb.tok0 + tt; const int tseq = jb.is_s ? tt : ci * SC_CH + tt;
;         const int gc = jb.h * 64 + c;
;         const bf16_t* zr = Q.z + (size_t)tok * DIN + gc;
;         L.r = *(const u32x2*)zr; L.k = *(const u32x2*)(zr + 512); L.v = *(const u32x2*)(zr + 1024);
;         if (tseq > 0) { L.rp = *(const u32x2*)(zr - DIN); L.kp = *(const u32x2*)(zr - DIN + 512); L.vp = *(const u32x2*)(zr - DIN + 1024); }
;         else if (jb.is_s) { const float* sp = Q.st_shift + (size_t)jb.seq * DSH + gc; L.fr = *(const f32x4*)sp; L.fk = *(const f32x4*)(sp + 512); L.fv = *(const f32x4*)(sp + 1024); }
;         L.sw = *(const u32x2*)(Q.sw + (size_t)tok * 512 + gc); L.sa = *(const u32x2*)(Q.sa + (size_t)tok * 512 + gc);
;     }
; }
; __device__ __forceinline__ f32x4 cv_bf4(const u32x2 w) { return (f32x4){bflo(w.x), bfhi(w.x), bflo(w.y), bfhi(w.y)}; }
; __device__ __forceinline__ void scan_finish(const ScanPtrs& Q, int J, int ci, unsigned char* buf, int ltid, const LStage& L, int toff) {
;     const Job jb = job_decode(J, ci);
;     const int tt = (ltid >> 4) + toff, c = (ltid & 15) * 4;
;     if (tt < jb.nsteps) {
;         const int tok = jb.tok0 + tt; const int tseq = jb.is_s ? tt : ci * SC_CH + tt;
;         const int gc = jb.h * 64 + c;
;         f32x4 r = cv_bf4(L.r), k0 = cv_bf4(L.k), v = cv_bf4(L.v), rp, kp, vp;
;         if (tseq > 0) { rp = cv_bf4(L.rp); kp = cv_bf4(L.kp); vp = cv_bf4(L.vp); }
;         else if (jb.is_s) { rp = L.fr; kp = L.fk; vp = L.fv; }
.LBB0_475:
	s_add_i32 s8, s64, 1
	s_cmpk_gt_i32 s51, 0xff
	s_cselect_b64 s[68:69], -1, 0
	s_cmpk_lt_i32 s51, 0x100
	s_cselect_b64 s[66:67], -1, 0
	s_and_b64 s[6:7], s[66:67], exec
	s_cselect_b32 s6, 64, 1
	s_cmp_lt_i32 s8, s6
	s_cselect_b32 s84, s8, 0
	s_cselect_b32 s85, 0, s46
	s_and_saveexec_b64 s[6:7], s[10:11]
	s_xor_b64 s[70:71], exec, s[6:7]
	s_cbranch_execz .LBB0_522
	v_cmp_gt_i32_e32 vcc, s77, v94
	s_and_saveexec_b64 s[72:73], vcc
	s_cbranch_execz .LBB0_501
	v_cmp_lt_i32_e64 s[16:17], s53, v94
	v_cmp_gt_i32_e32 vcc, s76, v94
	s_and_saveexec_b64 s[6:7], vcc
	s_xor_b64 s[18:19], exec, s[6:7]
	v_lshlrev_b32_e32 v18, 6, v94
	v_and_b32_e32 v18, 0xfffff800, v18
	v_lshl_add_u32 v122, v95, 5, v18
	s_or_saveexec_b64 s[18:19], s[18:19]
	v_mov_b32_e32 v18, 32
	s_xor_b64 exec, exec, s[18:19]
	s_cbranch_execz .Lxs_0
	v_add_u32_e32 v18, 0xffffff00, v94
	v_lshrrev_b32_e32 v18, 2, v18
	v_and_b32_e32 v18, 0x3ffffff8, v18
	v_add_u32_e32 v122, 0x4000, v18
	v_mov_b32_e32 v18, 8
.Lxs_0:
	s_or_b64 exec, exec, s[18:19]
	s_add_i32 s6, s83, 2
	s_mul_hi_u32 s7, s6, 0xaaaaaaab
	s_lshr_b32 s7, s7, 1
	s_mul_i32 s7, s7, 3
	s_sub_i32 s6, s6, s7
	s_mul_i32 s6, s6, 0xa800
	s_add_i32 s6, s6, 0
	v_and_b32_e32 v121, 3, v94
	v_bfe_u32 v91, v94, 2, 3
	v_cmp_lt_u32_e32 vcc, v96, v18
	v_lshlrev_b32_e32 v120, 5, v95
	s_and_saveexec_b64 s[74:75], vcc
	s_cbranch_execz .LBB0_492
	v_cndmask_b32_e64 v18, v120, 0, s[16:17]
	v_cmp_le_i32_e32 vcc, v18, v98
	s_and_saveexec_b64 s[8:9], vcc
	s_xor_b64 s[18:19], exec, s[8:9]
	s_cbranch_execz .LBB0_486
	v_mov_b32_e32 v20, v19
	v_mov_b32_e32 v21, v19
	v_mov_b32_e32 v18, v19
	v_mov_b64_e32 v[48:49], v[20:21]
	v_mov_b64_e32 v[52:53], v[20:21]
	v_mov_b64_e32 v[28:29], v[20:21]
	v_mov_b64_e32 v[46:47], v[18:19]
	v_mov_b64_e32 v[50:51], v[18:19]
	v_mov_b64_e32 v[26:27], v[18:19]
	s_and_saveexec_b64 s[20:21], s[16:17]
	s_cbranch_execz .LBB0_485
	s_waitcnt vmcnt(4)
	v_mov_b64_e32 v[48:49], v[8:9]
	s_waitcnt vmcnt(3)
	v_mov_b64_e32 v[52:53], v[12:13]
	s_waitcnt vmcnt(2)
	v_mov_b64_e32 v[28:29], v[16:17]
	v_mov_b64_e32 v[46:47], v[6:7]
	v_mov_b64_e32 v[50:51], v[10:11]
	v_mov_b64_e32 v[26:27], v[14:15]

; __device__ __forceinline__ f32x4 cv_bf4(const u32x2 w) { return (f32x4){bflo(w.x), bfhi(w.x), bflo(w.y), bfhi(w.y)}; }
; __device__ __forceinline__ void scan_finish(const ScanPtrs& Q, int J, int ci, unsigned char* buf, int ltid, const LStage& L, int toff) {
;     ...
;     if (tt < jb.nsteps) {
;         const int tok = jb.tok0 + tt; const int tseq = jb.is_s ? tt : ci * SC_CH + tt;
;         const int gc = jb.h * 64 + c;
;         f32x4 r = cv_bf4(L.r), k0 = cv_bf4(L.k), v = cv_bf4(L.v), rp, kp, vp;
;         if (tseq > 0) { rp = cv_bf4(L.rp); kp = cv_bf4(L.kp); vp = cv_bf4(L.vp); }
;         else if (jb.is_s) { rp = L.fr; kp = L.fk; vp = L.fv; }
;         else { rp = (f32x4){0.f, 0.f, 0.f, 0.f}; kp = rp; vp = rp; }
.LBB0_492:
	s_or_b64 exec, exec, s[74:75]
	s_nor_b64 s[8:9], s[16:17], s[12:13]
	v_cndmask_b32_e64 v18, 64, 1, s[16:17]
	s_and_saveexec_b64 s[22:23], s[8:9]
	s_cbranch_execz .LBB0_500
	v_cmp_gt_i32_e32 vcc, v120, v104
	s_andn2_b64 s[100:101], exec, vcc
	s_cbranch_scc0 .Lzs_0
	v_mov_b32_e32 v48, 0
	v_mov_b32_e32 v49, 0
	v_mov_b32_e32 v50, 0
	v_mov_b32_e32 v51, 0
	v_mov_b32_e32 v52, 0
	v_mov_b32_e32 v92, 0
	v_mov_b32_e32 v53, 0
	v_mov_b32_e32 v93, 0
	v_mov_b32_e32 v44, 0
	v_mov_b32_e32 v45, 0
	v_mov_b32_e32 v46, 0
	v_mov_b32_e32 v47, 0
.Lzs_0:
	s_and_saveexec_b64 s[16:17], vcc
	s_cbranch_execz .LBB0_495
	s_waitcnt vmcnt(4)
	v_lshlrev_b32_e32 v44, 16, v54
	v_and_b32_e32 v45, 0xffff0000, v54
	v_lshlrev_b32_e32 v46, 16, v55
	v_and_b32_e32 v47, 0xffff0000, v55
	s_waitcnt vmcnt(3)
	v_lshlrev_b32_e32 v52, 16, v58
	v_and_b32_e32 v92, 0xffff0000, v58
	v_lshlrev_b32_e32 v53, 16, v59
	v_and_b32_e32 v93, 0xffff0000, v59
	s_waitcnt vmcnt(2)
	v_lshlrev_b32_e32 v48, 16, v66
	v_and_b32_e32 v49, 0xffff0000, v66
	v_lshlrev_b32_e32 v50, 16, v67
	v_and_b32_e32 v51, 0xffff0000, v67

; __device__ __forceinline__ float bflo(unsigned w) { return __uint_as_float(w << 16); }
; __device__ __forceinline__ Job job_decode(int J, int ci) {
;     Job j;
;     if (J < 256) { const int pair = J >> 2; j.is_s = 0; j.seq = pair >> 3; j.h = pair & 7; j.rs = J & 3; j.tok0 = j.seq * SEQ + ci * SC_CH; j.nsteps = SC_CH; j.first = ci == 0; j.last = ci == SEQ / SC_CH - 1; }
;     else { const int Js = J - 256, pair = Js >> 2; j.is_s = 1; j.seq = pair >> 3; j.h = pair & 7; j.rs = Js & 3; j.tok0 = T_P + j.seq * DSEQ; j.nsteps = 8; j.first = 1; j.last = 1; }
;     return j;
; }
; __device__ __forceinline__ void scan_issue(const ScanPtrs& Q, int J, int ci, int ltid, LStage& L, int toff) {
;     const Job jb = job_decode(J, ci);
;     const int tt = (ltid >> 4) + toff, c = (ltid & 15) * 4;
;     if (tt < jb.nsteps) {
;         const int tok = jb.tok0 + tt; const int tseq = jb.is_s ? tt : ci * SC_CH + tt;
;         const int gc = jb.h * 64 + c;
;         const bf16_t* zr = Q.z + (size_t)tok * DIN + gc;
;         L.r = *(const u32x2*)zr; L.k = *(const u32x2*)(zr + 512); L.v = *(const u32x2*)(zr + 1024);
;         if (tseq > 0) { L.rp = *(const u32x2*)(zr - DIN); L.kp = *(const u32x2*)(zr - DIN + 512); L.vp = *(const u32x2*)(zr - DIN + 1024); }
;         else if (jb.is_s) { const float* sp = Q.st_shift + (size_t)jb.seq * DSH + gc; L.fr = *(const f32x4*)sp; L.fk = *(const f32x4*)(sp + 512); L.fv = *(const f32x4*)(sp + 1024); }
;         L.sw = *(const u32x2*)(Q.sw + (size_t)tok * 512 + gc); L.sa = *(const u32x2*)(Q.sa + (size_t)tok * 512 + gc);
;     }
; }
; __device__ __forceinline__ f32x4 cv_bf4(const u32x2 w) { return (f32x4){bflo(w.x), bfhi(w.x), bflo(w.y), bfhi(w.y)}; }
; __device__ __forceinline__ void scan_finish(const ScanPtrs& Q, int J, int ci, unsigned char* buf, int ltid, const LStage& L, int toff) {
;     const Job jb = job_decode(J, ci);
;     const int tt = (ltid >> 4) + toff, c = (ltid & 15) * 4;
;     if (tt < jb.nsteps) {
;         const int tok = jb.tok0 + tt; const int tseq = jb.is_s ? tt : ci * SC_CH + tt;
;         const int gc = jb.h * 64 + c;
;         f32x4 r = cv_bf4(L.r), k0 = cv_bf4(L.k), v = cv_bf4(L.v), rp, kp, vp;
;         if (tseq > 0) { rp = cv_bf4(L.rp); kp = cv_bf4(L.kp); vp = cv_bf4(L.vp); }
;         else if (jb.is_s) { rp = L.fr; kp = L.fk; vp = L.fv; }
.LBB0_1616:
	s_add_i32 s14, s60, 1
	s_cmpk_gt_i32 s53, 0xff
	s_cselect_b64 s[66:67], -1, 0
	s_cmpk_lt_i32 s53, 0x100
	s_cselect_b64 s[62:63], -1, 0
	s_and_b64 s[6:7], s[62:63], exec
	s_cselect_b32 s6, 64, 1
	s_cmp_lt_i32 s14, s6
	s_cselect_b64 s[64:65], -1, 0
	s_and_b64 s[6:7], s[64:65], exec
	s_cselect_b32 s85, s14, 0
	s_cselect_b32 s86, 0, s46
	s_and_saveexec_b64 s[6:7], s[10:11]
	s_xor_b64 s[68:69], exec, s[6:7]
	s_cbranch_execz .LBB0_1663
	v_cmp_gt_i32_e32 vcc, s76, v94
	s_and_saveexec_b64 s[70:71], vcc
	s_cbranch_execz .LBB0_1642
	v_cmp_lt_i32_e64 s[14:15], s74, v94
	v_cmp_gt_i32_e32 vcc, s75, v94
	s_and_saveexec_b64 s[6:7], vcc
	s_xor_b64 s[16:17], exec, s[6:7]
	v_lshlrev_b32_e32 v18, 6, v94
	v_and_b32_e32 v18, 0xfffff800, v18
	v_lshl_add_u32 v122, v95, 5, v18
	s_or_saveexec_b64 s[16:17], s[16:17]
	v_mov_b32_e32 v18, 32
	s_xor_b64 exec, exec, s[16:17]
	s_cbranch_execz .Lxs_1
	v_add_u32_e32 v18, 0xffffff00, v94
	v_lshrrev_b32_e32 v18, 2, v18
	v_and_b32_e32 v18, 0x3ffffff8, v18
	v_add_u32_e32 v122, 0x4000, v18
	v_mov_b32_e32 v18, 8
.Lxs_1:
	s_or_b64 exec, exec, s[16:17]
	s_add_i32 s6, s84, 2
	s_mul_hi_u32 s7, s6, 0xaaaaaaab
	s_lshr_b32 s7, s7, 1
	s_mul_i32 s7, s7, 3
	s_sub_i32 s6, s6, s7
	s_mul_i32 s6, s6, 0xa800
	s_add_i32 s6, s6, 0
	v_and_b32_e32 v121, 3, v94
	v_bfe_u32 v91, v94, 2, 3
	v_cmp_lt_u32_e32 vcc, v96, v18
	v_lshlrev_b32_e32 v120, 5, v95
	s_and_saveexec_b64 s[72:73], vcc
	s_cbranch_execz .LBB0_1633
	v_cndmask_b32_e64 v18, v120, 0, s[14:15]
	v_cmp_le_i32_e32 vcc, v18, v98
	s_and_saveexec_b64 s[16:17], vcc
	s_xor_b64 s[16:17], exec, s[16:17]
	s_cbranch_execz .LBB0_1627
	v_mov_b32_e32 v20, v19
	v_mov_b32_e32 v21, v19
	v_mov_b32_e32 v18, v19
	v_mov_b64_e32 v[48:49], v[20:21]
	v_mov_b64_e32 v[52:53], v[20:21]
	v_mov_b64_e32 v[28:29], v[20:21]
	v_mov_b64_e32 v[46:47], v[18:19]
	v_mov_b64_e32 v[50:51], v[18:19]
	v_mov_b64_e32 v[26:27], v[18:19]
	s_and_saveexec_b64 s[18:19], s[14:15]
	s_cbranch_execz .LBB0_1626
	s_waitcnt vmcnt(4)
	v_mov_b64_e32 v[48:49], v[8:9]
	s_waitcnt vmcnt(3)
	v_mov_b64_e32 v[52:53], v[12:13]
	s_waitcnt vmcnt(2)
	v_mov_b64_e32 v[28:29], v[16:17]
	v_mov_b64_e32 v[46:47], v[6:7]
	v_mov_b64_e32 v[50:51], v[10:11]
	v_mov_b64_e32 v[26:27], v[14:15]

; __device__ __forceinline__ f32x4 cv_bf4(const u32x2 w) { return (f32x4){bflo(w.x), bfhi(w.x), bflo(w.y), bfhi(w.y)}; }
; __device__ __forceinline__ void scan_finish(const ScanPtrs& Q, int J, int ci, unsigned char* buf, int ltid, const LStage& L, int toff) {
;     ...
;     if (tt < jb.nsteps) {
;         const int tok = jb.tok0 + tt; const int tseq = jb.is_s ? tt : ci * SC_CH + tt;
;         const int gc = jb.h * 64 + c;
;         f32x4 r = cv_bf4(L.r), k0 = cv_bf4(L.k), v = cv_bf4(L.v), rp, kp, vp;
;         if (tseq > 0) { rp = cv_bf4(L.rp); kp = cv_bf4(L.kp); vp = cv_bf4(L.vp); }
;         else if (jb.is_s) { rp = L.fr; kp = L.fk; vp = L.fv; }
;         else { rp = (f32x4){0.f, 0.f, 0.f, 0.f}; kp = rp; vp = rp; }
.LBB0_1633:
	s_or_b64 exec, exec, s[72:73]
	s_nor_b64 s[16:17], s[14:15], s[8:9]
	v_cndmask_b32_e64 v18, 64, 1, s[14:15]
	s_and_saveexec_b64 s[20:21], s[16:17]
	s_cbranch_execz .LBB0_1641
	v_cmp_gt_i32_e32 vcc, v120, v104
	s_andn2_b64 s[100:101], exec, vcc
	s_cbranch_scc0 .Lzs_1
	v_mov_b32_e32 v48, 0
	v_mov_b32_e32 v49, 0
	v_mov_b32_e32 v50, 0
	v_mov_b32_e32 v51, 0
	v_mov_b32_e32 v52, 0
	v_mov_b32_e32 v92, 0
	v_mov_b32_e32 v53, 0
	v_mov_b32_e32 v93, 0
	v_mov_b32_e32 v44, 0
	v_mov_b32_e32 v45, 0
	v_mov_b32_e32 v46, 0
	v_mov_b32_e32 v47, 0
.Lzs_1:
	s_and_saveexec_b64 s[14:15], vcc
	s_cbranch_execz .LBB0_1636
	s_waitcnt vmcnt(4)
	v_lshlrev_b32_e32 v44, 16, v54
	v_and_b32_e32 v45, 0xffff0000, v54
	v_lshlrev_b32_e32 v46, 16, v55
	v_and_b32_e32 v47, 0xffff0000, v55
	s_waitcnt vmcnt(3)
	v_lshlrev_b32_e32 v52, 16, v58
	v_and_b32_e32 v92, 0xffff0000, v58
	v_lshlrev_b32_e32 v53, 16, v59
	v_and_b32_e32 v93, 0xffff0000, v59
	s_waitcnt vmcnt(2)
	v_lshlrev_b32_e32 v48, 16, v66
	v_and_b32_e32 v49, 0xffff0000, v66
	v_lshlrev_b32_e32 v50, 16, v67
	v_and_b32_e32 v51, 0xffff0000, v67
